# plus: in the tail loops waves 4-7 run softmax+PV before QK (opposite order to waves 0-3 on the same SIMD)
# baseline (speedup 1.0000x reference)
.LBB0_678:
	s_add_i32 s57, s61, 64
	s_cmp_le_i32 s57, s40
	s_cselect_b64 s[4:5], -1, 0
	s_and_b64 s[4:5], s[14:15], s[4:5]
	s_mov_b64 s[98:99], s[4:5]
	s_cmp_ge_u32 s33, 4
	s_cbranch_scc1 .Lpar_f0_c
	s_andn2_b64 vcc, exec, s[4:5]
	s_cbranch_vccnz .LBB0_681
.Lpar_f0_qk:
	v_add_u32_e32 v126, s55, v148
	v_add_u32_e32 v12, s54, v158
	ds_read_b128 v[190:193], v126
	ds_read_b128 v[78:81], v12 offset:43008
	ds_read_b128 v[82:85], v12 offset:43040
	ds_read_b128 v[86:89], v12 offset:43072
	ds_read_b128 v[90:93], v12 offset:43104
	ds_read_b128 v[194:197], v126 offset:4608
	ds_read_b128 v[94:97], v12 offset:43136
	ds_read_b128 v[98:101], v12 offset:43168
	ds_read_b128 v[102:105], v12 offset:43200
	ds_read_b128 v[106:109], v12 offset:43232
	ds_read_b128 v[198:201], v126 offset:32
	ds_read_b128 v[202:205], v126 offset:4640
	ds_read_b128 v[206:209], v126 offset:64
	ds_read_b128 v[210:213], v126 offset:4672
	ds_read_b128 v[214:217], v126 offset:96
	s_add_i32 s4, s61, 0x7f
	s_waitcnt lgkmcnt(10)
	v_mfma_f32_32x32x16_bf16 v[78:93], v[190:193], v[0:3], v[78:93]
	ds_read_b128 v[222:225], v126 offset:4704
	s_cmp_le_i32 s4, s40
	s_waitcnt lgkmcnt(6)
	v_mfma_f32_32x32x16_bf16 v[94:109], v[194:197], v[0:3], v[94:109]
	s_waitcnt lgkmcnt(5)
	v_mfma_f32_32x32x16_bf16 v[78:93], v[198:201], v[4:7], v[78:93]
	s_waitcnt lgkmcnt(4)
	v_mfma_f32_32x32x16_bf16 v[94:109], v[202:205], v[4:7], v[94:109]
	s_waitcnt lgkmcnt(3)
	v_mfma_f32_32x32x16_bf16 v[78:93], v[206:209], v[8:11], v[78:93]
	s_waitcnt lgkmcnt(2)
	v_mfma_f32_32x32x16_bf16 v[94:109], v[210:213], v[8:11], v[94:109]
	s_waitcnt lgkmcnt(1)
	v_mfma_f32_32x32x16_bf16 v[78:93], v[214:217], v[110:113], v[78:93]
	s_waitcnt lgkmcnt(0)
	v_mfma_f32_32x32x16_bf16 v[94:109], v[222:225], v[110:113], v[94:109]
	s_cbranch_scc1 .LBB0_681
	v_add_u32_e32 v12, s61, v156
	v_add_u32_e32 v123, 0x60, v12
	v_add_u32_e32 v122, 64, v12
	v_cmp_le_i32_e32 vcc, v123, v157
	s_nop 6
	v_cndmask_b32_e32 v94, v220, v94, vcc
	v_cmp_lt_i32_e32 vcc, v122, v157
	s_nop 1
	v_cndmask_b32_e32 v79, v220, v79, vcc
	v_cmp_le_i32_e32 vcc, v122, v157
	v_add_u32_e32 v122, 0x61, v12
	s_nop 0
	v_cndmask_b32_e32 v78, v220, v78, vcc
	v_cmp_le_i32_e32 vcc, v122, v157
	v_add_u32_e32 v122, 0x42, v12
	s_nop 0
	v_cndmask_b32_e32 v95, v220, v95, vcc
	v_cmp_le_i32_e32 vcc, v122, v157
	v_add_u32_e32 v122, 0x62, v12
	s_nop 0
	v_cndmask_b32_e32 v80, v220, v80, vcc
	v_cmp_le_i32_e32 vcc, v122, v157
	v_add_u32_e32 v122, 0x43, v12
	s_nop 0
	v_cndmask_b32_e32 v96, v220, v96, vcc
	v_cmp_le_i32_e32 vcc, v122, v157
	v_add_u32_e32 v122, 0x63, v12
	s_nop 0
	v_cndmask_b32_e32 v81, v220, v81, vcc
	v_cmp_le_i32_e32 vcc, v122, v157
	v_add_u32_e32 v122, 0x48, v12
	s_nop 0
	v_cndmask_b32_e32 v97, v220, v97, vcc
	v_cmp_le_i32_e32 vcc, v122, v157
	v_add_u32_e32 v122, 0x68, v12
	s_nop 0
	v_cndmask_b32_e32 v82, v220, v82, vcc
	v_cmp_le_i32_e32 vcc, v122, v157
	v_add_u32_e32 v122, 0x49, v12
	s_nop 0
	v_cndmask_b32_e32 v98, v220, v98, vcc
	v_cmp_le_i32_e32 vcc, v122, v157
	v_add_u32_e32 v122, 0x69, v12
	s_nop 0
	v_cndmask_b32_e32 v83, v220, v83, vcc
	v_cmp_le_i32_e32 vcc, v122, v157
	v_add_u32_e32 v122, 0x4a, v12
	s_nop 0
	v_cndmask_b32_e32 v99, v220, v99, vcc
	v_cmp_le_i32_e32 vcc, v122, v157
	v_add_u32_e32 v122, 0x6a, v12
	s_nop 0
	v_cndmask_b32_e32 v84, v220, v84, vcc
	v_cmp_le_i32_e32 vcc, v122, v157
	v_add_u32_e32 v122, 0x4b, v12
	s_nop 0
	v_cndmask_b32_e32 v100, v220, v100, vcc
	v_cmp_le_i32_e32 vcc, v122, v157
	v_add_u32_e32 v122, 0x6b, v12
	s_nop 0
	v_cndmask_b32_e32 v85, v220, v85, vcc
	v_cmp_le_i32_e32 vcc, v122, v157
	v_add_u32_e32 v122, 0x50, v12
	s_nop 0
	v_cndmask_b32_e32 v101, v220, v101, vcc
	v_cmp_le_i32_e32 vcc, v122, v157
	v_add_u32_e32 v122, 0x70, v12
	s_nop 0
	v_cndmask_b32_e32 v86, v220, v86, vcc
	v_cmp_le_i32_e32 vcc, v122, v157
	v_add_u32_e32 v122, 0x51, v12
	s_nop 0
	v_cndmask_b32_e32 v102, v220, v102, vcc
	v_cmp_le_i32_e32 vcc, v122, v157
	v_add_u32_e32 v122, 0x71, v12
	s_nop 0
	v_cndmask_b32_e32 v87, v220, v87, vcc
	v_cmp_le_i32_e32 vcc, v122, v157
	v_add_u32_e32 v122, 0x52, v12
	s_nop 0
	v_cndmask_b32_e32 v103, v220, v103, vcc
	v_cmp_le_i32_e32 vcc, v122, v157
	v_add_u32_e32 v122, 0x72, v12
	s_nop 0
	v_cndmask_b32_e32 v88, v220, v88, vcc
	v_cmp_le_i32_e32 vcc, v122, v157
	v_add_u32_e32 v122, 0x53, v12
	s_nop 0
	v_cndmask_b32_e32 v104, v220, v104, vcc
	v_cmp_le_i32_e32 vcc, v122, v157
	v_add_u32_e32 v122, 0x73, v12
	s_nop 0
	v_cndmask_b32_e32 v89, v220, v89, vcc
	v_cmp_le_i32_e32 vcc, v122, v157
	v_add_u32_e32 v122, 0x58, v12
	s_nop 0
	v_cndmask_b32_e32 v105, v220, v105, vcc
	v_cmp_le_i32_e32 vcc, v122, v157
	v_add_u32_e32 v122, 0x78, v12
	s_nop 0
	v_cndmask_b32_e32 v90, v220, v90, vcc
	v_cmp_le_i32_e32 vcc, v122, v157
	v_add_u32_e32 v122, 0x59, v12
	s_nop 0
	v_cndmask_b32_e32 v106, v220, v106, vcc
	v_cmp_le_i32_e32 vcc, v122, v157
	v_add_u32_e32 v122, 0x79, v12
	s_nop 0
	v_cndmask_b32_e32 v91, v220, v91, vcc
	v_cmp_le_i32_e32 vcc, v122, v157
	v_add_u32_e32 v122, 0x5a, v12
	s_nop 0
	v_cndmask_b32_e32 v107, v220, v107, vcc
	v_cmp_le_i32_e32 vcc, v122, v157
	v_add_u32_e32 v122, 0x7a, v12
	s_nop 0
	v_cndmask_b32_e32 v92, v220, v92, vcc
	v_cmp_le_i32_e32 vcc, v122, v157
	v_add_u32_e32 v122, 0x5b, v12
	v_add_u32_e32 v12, 0x7b, v12
	v_cndmask_b32_e32 v108, v220, v108, vcc
	v_cmp_le_i32_e32 vcc, v122, v157
	s_nop 1
	v_cndmask_b32_e32 v93, v220, v93, vcc
	v_cmp_le_i32_e32 vcc, v12, v157
	s_nop 1
	v_cndmask_b32_e32 v109, v220, v109, vcc
.LBB0_681:
	s_cmp_ge_u32 s33, 4
	s_cbranch_scc1 .LBB0_685

.LBB0_684:
	v_sub_f32_e32 v12, v46, v160
	v_exp_f32_e32 v46, v12
	v_sub_f32_e32 v12, v62, v160
	v_exp_f32_e32 v62, v12
	v_sub_f32_e32 v12, v47, v160
	v_sub_f32_e32 v47, v63, v160
	v_exp_f32_e32 v12, v12
	v_exp_f32_e32 v122, v47
	v_add_f32_e32 v123, v62, v46
	v_sub_f32_e32 v47, v48, v160
	v_exp_f32_e32 v48, v47
	v_pk_add_f32 v[124:125], v[122:123], v[12:13]
	v_sub_f32_e32 v47, v64, v160
	v_pk_add_f32 v[124:125], v[124:125], v[124:125] op_sel_hi:[0,1]
	v_exp_f32_e32 v64, v47
	v_sub_f32_e32 v47, v49, v160
	v_exp_f32_e32 v124, v47
	v_sub_f32_e32 v47, v65, v160
	v_exp_f32_e32 v128, v47
	v_add_f32_e32 v129, v64, v48
	v_sub_f32_e32 v47, v50, v160
	v_exp_f32_e32 v50, v47
	v_pk_add_f32 v[126:127], v[128:129], v[124:125]
	v_sub_f32_e32 v47, v66, v160
	v_pk_add_f32 v[126:127], v[126:127], v[126:127] op_sel_hi:[0,1]
	v_exp_f32_e32 v66, v47
	v_sub_f32_e32 v47, v51, v160
	v_exp_f32_e32 v126, v47
	v_sub_f32_e32 v47, v67, v160
	v_exp_f32_e32 v130, v47
	v_add_f32_e32 v131, v66, v50
	v_sub_f32_e32 v47, v52, v160
	v_exp_f32_e32 v52, v47
	v_pk_add_f32 v[132:133], v[130:131], v[126:127]
	v_sub_f32_e32 v47, v68, v160
	v_pk_add_f32 v[132:133], v[132:133], v[132:133] op_sel_hi:[0,1]
	v_exp_f32_e32 v68, v47
	v_sub_f32_e32 v47, v53, v160
	v_exp_f32_e32 v132, v47
	v_sub_f32_e32 v47, v69, v160
	v_exp_f32_e32 v150, v47
	v_add_f32_e32 v151, v68, v52
	v_sub_f32_e32 v47, v54, v160
	v_exp_f32_e32 v54, v47
	v_pk_add_f32 v[162:163], v[150:151], v[132:133]
	v_sub_f32_e32 v47, v70, v160
	v_pk_add_f32 v[168:169], v[162:163], v[162:163] op_sel_hi:[0,1]
	v_exp_f32_e32 v70, v47
	v_sub_f32_e32 v47, v55, v160
	v_exp_f32_e32 v168, v47
	v_sub_f32_e32 v47, v71, v160
	v_exp_f32_e32 v170, v47
	v_add_f32_e32 v171, v70, v54
	v_sub_f32_e32 v47, v56, v160
	v_exp_f32_e32 v56, v47
	v_pk_add_f32 v[162:163], v[170:171], v[168:169]
	v_sub_f32_e32 v47, v72, v160
	v_pk_add_f32 v[172:173], v[162:163], v[162:163] op_sel_hi:[0,1]
	v_exp_f32_e32 v72, v47
	v_sub_f32_e32 v47, v57, v160
	v_exp_f32_e32 v172, v47
	v_sub_f32_e32 v47, v73, v160
	v_exp_f32_e32 v174, v47
	v_add_f32_e32 v175, v72, v56
	v_sub_f32_e32 v47, v58, v160
	v_exp_f32_e32 v58, v47
	v_pk_add_f32 v[162:163], v[174:175], v[172:173]
	v_sub_f32_e32 v47, v74, v160
	v_pk_add_f32 v[176:177], v[162:163], v[162:163] op_sel_hi:[0,1]
	v_exp_f32_e32 v74, v47
	v_sub_f32_e32 v47, v59, v160
	v_exp_f32_e32 v176, v47
	v_sub_f32_e32 v47, v75, v160
	v_exp_f32_e32 v178, v47
	v_sub_f32_e32 v47, v60, v160
	v_exp_f32_e32 v60, v47
	v_sub_f32_e32 v47, v76, v160
	v_exp_f32_e32 v76, v47
	v_sub_f32_e32 v47, v61, v160
	v_sub_f32_e32 v63, v77, v160
	v_exp_f32_e32 v61, v47
	v_exp_f32_e32 v77, v63
	v_add_f32_e32 v179, v74, v58
	v_pk_add_f32 v[162:163], v[178:179], v[176:177]
	v_add_f32_e32 v165, v76, v60
	v_pk_add_f32 v[162:163], v[162:163], v[162:163] op_sel_hi:[0,1]
	v_mov_b32_e32 v164, v77
	v_mov_b32_e32 v162, v61
	v_pk_add_f32 v[162:163], v[164:165], v[162:163]
	s_and_b32 s4, s60, 0x2000
	v_mov_b32_e32 v47, v12
	v_add_f32_e32 v149, v162, v163
	v_cvt_pk_bf16_f32 v162, v46, v12
	v_add_u32_e32 v12, s4, v159
	v_mov_b32_e32 v51, v126
	v_mov_b32_e32 v55, v168
	v_mov_b32_e32 v57, v172
	v_mov_b32_e32 v63, v122
	v_mov_b32_e32 v65, v128
	v_mov_b32_e32 v67, v130
	v_mov_b32_e32 v71, v170
	v_mov_b32_e32 v73, v174
	v_cvt_pk_bf16_f32 v164, v50, v126
	v_cvt_pk_bf16_f32 v126, v62, v122
	v_cvt_pk_bf16_f32 v127, v64, v128
	v_cvt_pk_bf16_f32 v128, v66, v130
	v_cvt_pk_bf16_f32 v130, v54, v168
	v_cvt_pk_bf16_f32 v131, v56, v172
	v_cvt_pk_bf16_f32 v122, v70, v170
	v_cvt_pk_bf16_f32 v123, v72, v174
	ds_read_b64_tr_b16 v[168:169], v12 offset:26624
	ds_read_b64_tr_b16 v[170:171], v12 offset:27136
	ds_read_b64_tr_b16 v[172:173], v12 offset:30720
	ds_read_b64_tr_b16 v[174:175], v12 offset:31232
	v_cvt_pk_bf16_f32 v163, v48, v124
	v_cvt_pk_bf16_f32 v165, v52, v132
	v_mov_b32_e32 v53, v132
	v_cvt_pk_bf16_f32 v132, v58, v176
	s_waitcnt lgkmcnt(2)
	v_mfma_f32_32x32x16_bf16 v[14:29], v[168:171], v[162:165], v[14:29]
	v_cvt_pk_bf16_f32 v133, v60, v61
	v_cvt_pk_bf16_f32 v129, v68, v150
	v_mov_b32_e32 v49, v124
	v_cvt_pk_bf16_f32 v124, v74, v178
	v_cvt_pk_bf16_f32 v125, v76, v77
	v_mov_b32_e32 v59, v176
	v_mov_b32_e32 v69, v150
	s_waitcnt lgkmcnt(0)
	v_mfma_f32_32x32x16_bf16 v[30:45], v[172:175], v[162:165], v[30:45]
	ds_read_b64_tr_b16 v[162:163], v12 offset:27648
	ds_read_b64_tr_b16 v[164:165], v12 offset:28160
	ds_read_b64_tr_b16 v[168:169], v12 offset:31744
	ds_read_b64_tr_b16 v[170:171], v12 offset:32256
	v_mov_b32_e32 v75, v178
	v_add_f32_e32 v161, v161, v149
	s_waitcnt lgkmcnt(2)
	v_mfma_f32_32x32x16_bf16 v[14:29], v[162:165], v[130:133], v[14:29]
	s_waitcnt lgkmcnt(0)
	v_mfma_f32_32x32x16_bf16 v[30:45], v[168:171], v[130:133], v[30:45]
	ds_read_b64_tr_b16 v[130:131], v12 offset:28672
	ds_read_b64_tr_b16 v[132:133], v12 offset:29184
	ds_read_b64_tr_b16 v[162:163], v12 offset:32768
	ds_read_b64_tr_b16 v[164:165], v12 offset:33280
	s_waitcnt lgkmcnt(2)
	v_mfma_f32_32x32x16_bf16 v[14:29], v[130:133], v[126:129], v[14:29]
	s_waitcnt lgkmcnt(0)
	v_mfma_f32_32x32x16_bf16 v[30:45], v[162:165], v[126:129], v[30:45]
	ds_read_b64_tr_b16 v[126:127], v12 offset:29696
	ds_read_b64_tr_b16 v[128:129], v12 offset:30208
	ds_read_b64_tr_b16 v[130:131], v12 offset:33792
	ds_read_b64_tr_b16 v[132:133], v12 offset:34304
	s_waitcnt lgkmcnt(2)
	v_mfma_f32_32x32x16_bf16 v[14:29], v[126:129], v[122:125], v[14:29]
	s_waitcnt lgkmcnt(0)
	v_mfma_f32_32x32x16_bf16 v[30:45], v[130:133], v[122:125], v[30:45]
	s_cmp_ge_u32 s33, 4
	s_cbranch_scc0 .LBB0_685
	s_andn2_b64 vcc, exec, s[98:99]
	s_cbranch_vccnz .LBB0_685
	s_branch .Lpar_f0_qk

.LBB0_697:
	s_add_i32 s13, s61, 0x80
	s_cmp_le_i32 s13, s40
	s_cselect_b64 s[16:17], -1, 0
	s_and_b64 s[10:11], s[10:11], s[16:17]
	s_mov_b64 s[100:101], s[10:11]
	s_cmp_ge_u32 s33, 4
	s_cbranch_scc1 .Lpar_f1_c
	s_andn2_b64 vcc, exec, s[10:11]
	s_cbranch_vccnz .LBB0_700
.Lpar_f1_qk:
	v_add_u32_e32 v126, s58, v148
	v_add_u32_e32 v12, s59, v158
	ds_read_b128 v[190:193], v126
	ds_read_b128 v[46:49], v12 offset:43008
	ds_read_b128 v[50:53], v12 offset:43040
	ds_read_b128 v[54:57], v12 offset:43072
	ds_read_b128 v[58:61], v12 offset:43104
	ds_read_b128 v[194:197], v126 offset:4608
	ds_read_b128 v[62:65], v12 offset:43136
	ds_read_b128 v[66:69], v12 offset:43168
	ds_read_b128 v[70:73], v12 offset:43200
	ds_read_b128 v[74:77], v12 offset:43232
	ds_read_b128 v[198:201], v126 offset:32
	ds_read_b128 v[202:205], v126 offset:4640
	ds_read_b128 v[206:209], v126 offset:64
	ds_read_b128 v[210:213], v126 offset:4672
	ds_read_b128 v[214:217], v126 offset:96
	s_add_i32 s10, s61, 0xbf
	s_waitcnt lgkmcnt(10)
	v_mfma_f32_32x32x16_bf16 v[46:61], v[190:193], v[0:3], v[46:61]
	ds_read_b128 v[222:225], v126 offset:4704
	s_cmp_le_i32 s10, s40
	s_waitcnt lgkmcnt(6)
	v_mfma_f32_32x32x16_bf16 v[62:77], v[194:197], v[0:3], v[62:77]
	s_waitcnt lgkmcnt(5)
	v_mfma_f32_32x32x16_bf16 v[46:61], v[198:201], v[4:7], v[46:61]
	s_waitcnt lgkmcnt(4)
	v_mfma_f32_32x32x16_bf16 v[62:77], v[202:205], v[4:7], v[62:77]
	s_waitcnt lgkmcnt(3)
	v_mfma_f32_32x32x16_bf16 v[46:61], v[206:209], v[8:11], v[46:61]
	s_waitcnt lgkmcnt(2)
	v_mfma_f32_32x32x16_bf16 v[62:77], v[210:213], v[8:11], v[62:77]
	s_waitcnt lgkmcnt(1)
	v_mfma_f32_32x32x16_bf16 v[46:61], v[214:217], v[110:113], v[46:61]
	s_waitcnt lgkmcnt(0)
	v_mfma_f32_32x32x16_bf16 v[62:77], v[222:225], v[110:113], v[62:77]
	s_cbranch_scc1 .LBB0_700
	v_add_u32_e32 v12, s61, v156
	v_add_u32_e32 v123, 0xa0, v12
	v_add_u32_e32 v122, 0x80, v12
	v_cmp_le_i32_e32 vcc, v123, v157
	s_nop 6
	v_cndmask_b32_e32 v62, v220, v62, vcc
	v_cmp_lt_i32_e32 vcc, v122, v157
	s_nop 1
	v_cndmask_b32_e32 v47, v220, v47, vcc
	v_cmp_le_i32_e32 vcc, v122, v157
	v_add_u32_e32 v122, 0xa1, v12
	s_nop 0
	v_cndmask_b32_e32 v46, v220, v46, vcc
	v_cmp_le_i32_e32 vcc, v122, v157
	v_add_u32_e32 v122, 0x82, v12
	s_nop 0
	v_cndmask_b32_e32 v63, v220, v63, vcc
	v_cmp_le_i32_e32 vcc, v122, v157
	v_add_u32_e32 v122, 0xa2, v12
	s_nop 0
	v_cndmask_b32_e32 v48, v220, v48, vcc
	v_cmp_le_i32_e32 vcc, v122, v157
	v_add_u32_e32 v122, 0x83, v12
	s_nop 0
	v_cndmask_b32_e32 v64, v220, v64, vcc
	v_cmp_le_i32_e32 vcc, v122, v157
	v_add_u32_e32 v122, 0xa3, v12
	s_nop 0
	v_cndmask_b32_e32 v49, v220, v49, vcc
	v_cmp_le_i32_e32 vcc, v122, v157
	v_add_u32_e32 v122, 0x88, v12
	s_nop 0
	v_cndmask_b32_e32 v65, v220, v65, vcc
	v_cmp_le_i32_e32 vcc, v122, v157
	v_add_u32_e32 v122, 0xa8, v12
	s_nop 0
	v_cndmask_b32_e32 v50, v220, v50, vcc
	v_cmp_le_i32_e32 vcc, v122, v157
	v_add_u32_e32 v122, 0x89, v12
	s_nop 0
	v_cndmask_b32_e32 v66, v220, v66, vcc
	v_cmp_le_i32_e32 vcc, v122, v157
	v_add_u32_e32 v122, 0xa9, v12
	s_nop 0
	v_cndmask_b32_e32 v51, v220, v51, vcc
	v_cmp_le_i32_e32 vcc, v122, v157
	v_add_u32_e32 v122, 0x8a, v12
	s_nop 0
	v_cndmask_b32_e32 v67, v220, v67, vcc
	v_cmp_le_i32_e32 vcc, v122, v157
	v_add_u32_e32 v122, 0xaa, v12
	s_nop 0
	v_cndmask_b32_e32 v52, v220, v52, vcc
	v_cmp_le_i32_e32 vcc, v122, v157
	v_add_u32_e32 v122, 0x8b, v12
	s_nop 0
	v_cndmask_b32_e32 v68, v220, v68, vcc
	v_cmp_le_i32_e32 vcc, v122, v157
	v_add_u32_e32 v122, 0xab, v12
	s_nop 0
	v_cndmask_b32_e32 v53, v220, v53, vcc
	v_cmp_le_i32_e32 vcc, v122, v157
	v_add_u32_e32 v122, 0x90, v12
	s_nop 0
	v_cndmask_b32_e32 v69, v220, v69, vcc
	v_cmp_le_i32_e32 vcc, v122, v157
	v_add_u32_e32 v122, 0xb0, v12
	s_nop 0
	v_cndmask_b32_e32 v54, v220, v54, vcc
	v_cmp_le_i32_e32 vcc, v122, v157
	v_add_u32_e32 v122, 0x91, v12
	s_nop 0
	v_cndmask_b32_e32 v70, v220, v70, vcc
	v_cmp_le_i32_e32 vcc, v122, v157
	v_add_u32_e32 v122, 0xb1, v12
	s_nop 0
	v_cndmask_b32_e32 v55, v220, v55, vcc
	v_cmp_le_i32_e32 vcc, v122, v157
	v_add_u32_e32 v122, 0x92, v12
	s_nop 0
	v_cndmask_b32_e32 v71, v220, v71, vcc
	v_cmp_le_i32_e32 vcc, v122, v157
	v_add_u32_e32 v122, 0xb2, v12
	s_nop 0
	v_cndmask_b32_e32 v56, v220, v56, vcc
	v_cmp_le_i32_e32 vcc, v122, v157
	v_add_u32_e32 v122, 0x93, v12
	s_nop 0
	v_cndmask_b32_e32 v72, v220, v72, vcc
	v_cmp_le_i32_e32 vcc, v122, v157
	v_add_u32_e32 v122, 0xb3, v12
	s_nop 0
	v_cndmask_b32_e32 v57, v220, v57, vcc
	v_cmp_le_i32_e32 vcc, v122, v157
	v_add_u32_e32 v122, 0x98, v12
	s_nop 0
	v_cndmask_b32_e32 v73, v220, v73, vcc
	v_cmp_le_i32_e32 vcc, v122, v157
	v_add_u32_e32 v122, 0xb8, v12
	s_nop 0
	v_cndmask_b32_e32 v58, v220, v58, vcc
	v_cmp_le_i32_e32 vcc, v122, v157
	v_add_u32_e32 v122, 0x99, v12
	s_nop 0
	v_cndmask_b32_e32 v74, v220, v74, vcc
	v_cmp_le_i32_e32 vcc, v122, v157
	v_add_u32_e32 v122, 0xb9, v12
	s_nop 0
	v_cndmask_b32_e32 v59, v220, v59, vcc
	v_cmp_le_i32_e32 vcc, v122, v157
	v_add_u32_e32 v122, 0x9a, v12
	s_nop 0
	v_cndmask_b32_e32 v75, v220, v75, vcc
	v_cmp_le_i32_e32 vcc, v122, v157
	v_add_u32_e32 v122, 0xba, v12
	s_nop 0
	v_cndmask_b32_e32 v60, v220, v60, vcc
	v_cmp_le_i32_e32 vcc, v122, v157
	v_add_u32_e32 v122, 0x9b, v12
	v_add_u32_e32 v12, 0xbb, v12
	v_cndmask_b32_e32 v76, v220, v76, vcc
	v_cmp_le_i32_e32 vcc, v122, v157
	s_nop 1
	v_cndmask_b32_e32 v61, v220, v61, vcc
	v_cmp_le_i32_e32 vcc, v12, v157
	s_nop 1
	v_cndmask_b32_e32 v77, v220, v77, vcc

.LBB0_703:
	v_sub_f32_e32 v12, v78, v160
	v_exp_f32_e32 v78, v12
	v_sub_f32_e32 v12, v94, v160
	v_exp_f32_e32 v94, v12
	v_sub_f32_e32 v12, v79, v160
	v_sub_f32_e32 v79, v95, v160
	v_exp_f32_e32 v12, v12
	v_exp_f32_e32 v122, v79
	v_add_f32_e32 v123, v94, v78
	v_sub_f32_e32 v79, v80, v160
	v_exp_f32_e32 v80, v79
	v_pk_add_f32 v[124:125], v[122:123], v[12:13]
	v_sub_f32_e32 v79, v96, v160
	v_pk_add_f32 v[124:125], v[124:125], v[124:125] op_sel_hi:[0,1]
	v_exp_f32_e32 v96, v79
	v_sub_f32_e32 v79, v81, v160
	v_exp_f32_e32 v124, v79
	v_sub_f32_e32 v79, v97, v160
	v_exp_f32_e32 v128, v79
	v_add_f32_e32 v129, v96, v80
	v_sub_f32_e32 v79, v82, v160
	v_exp_f32_e32 v82, v79
	v_pk_add_f32 v[126:127], v[128:129], v[124:125]
	v_sub_f32_e32 v79, v98, v160
	v_pk_add_f32 v[126:127], v[126:127], v[126:127] op_sel_hi:[0,1]
	v_exp_f32_e32 v98, v79
	v_sub_f32_e32 v79, v83, v160
	v_exp_f32_e32 v126, v79
	v_sub_f32_e32 v79, v99, v160
	v_exp_f32_e32 v130, v79
	v_add_f32_e32 v131, v98, v82
	v_sub_f32_e32 v79, v84, v160
	v_exp_f32_e32 v84, v79
	v_pk_add_f32 v[132:133], v[130:131], v[126:127]
	v_sub_f32_e32 v79, v100, v160
	v_pk_add_f32 v[132:133], v[132:133], v[132:133] op_sel_hi:[0,1]
	v_exp_f32_e32 v100, v79
	v_sub_f32_e32 v79, v85, v160
	v_exp_f32_e32 v132, v79
	v_sub_f32_e32 v79, v101, v160
	v_exp_f32_e32 v150, v79
	v_add_f32_e32 v151, v100, v84
	v_sub_f32_e32 v79, v86, v160
	v_exp_f32_e32 v86, v79
	v_pk_add_f32 v[162:163], v[150:151], v[132:133]
	v_sub_f32_e32 v79, v102, v160
	v_pk_add_f32 v[168:169], v[162:163], v[162:163] op_sel_hi:[0,1]
	v_exp_f32_e32 v102, v79
	v_sub_f32_e32 v79, v87, v160
	v_exp_f32_e32 v168, v79
	v_sub_f32_e32 v79, v103, v160
	v_exp_f32_e32 v170, v79
	v_add_f32_e32 v171, v102, v86
	v_sub_f32_e32 v79, v88, v160
	v_exp_f32_e32 v88, v79
	v_pk_add_f32 v[162:163], v[170:171], v[168:169]
	v_sub_f32_e32 v79, v104, v160
	v_pk_add_f32 v[172:173], v[162:163], v[162:163] op_sel_hi:[0,1]
	v_exp_f32_e32 v104, v79
	v_sub_f32_e32 v79, v89, v160
	v_exp_f32_e32 v172, v79
	v_sub_f32_e32 v79, v105, v160
	v_exp_f32_e32 v174, v79
	v_add_f32_e32 v175, v104, v88
	v_sub_f32_e32 v79, v90, v160
	v_exp_f32_e32 v90, v79
	v_pk_add_f32 v[162:163], v[174:175], v[172:173]
	v_sub_f32_e32 v79, v106, v160
	v_pk_add_f32 v[176:177], v[162:163], v[162:163] op_sel_hi:[0,1]
	v_exp_f32_e32 v106, v79
	v_sub_f32_e32 v79, v91, v160
	v_exp_f32_e32 v176, v79
	v_sub_f32_e32 v79, v107, v160
	v_exp_f32_e32 v178, v79
	v_sub_f32_e32 v79, v92, v160
	v_exp_f32_e32 v92, v79
	v_sub_f32_e32 v79, v108, v160
	v_exp_f32_e32 v108, v79
	v_sub_f32_e32 v79, v93, v160
	v_sub_f32_e32 v95, v109, v160
	v_exp_f32_e32 v93, v79
	v_exp_f32_e32 v109, v95
	v_add_f32_e32 v179, v106, v90
	v_pk_add_f32 v[162:163], v[178:179], v[176:177]
	v_add_f32_e32 v165, v108, v92
	v_pk_add_f32 v[162:163], v[162:163], v[162:163] op_sel_hi:[0,1]
	v_mov_b32_e32 v164, v109
	v_mov_b32_e32 v162, v93
	s_add_i32 s10, s60, 0x2000
	v_pk_add_f32 v[162:163], v[164:165], v[162:163]
	s_and_b32 s10, s10, 0x2000
	v_mov_b32_e32 v79, v12
	v_add_f32_e32 v149, v162, v163
	v_cvt_pk_bf16_f32 v162, v78, v12
	v_add_u32_e32 v12, s10, v159
	v_mov_b32_e32 v83, v126
	v_mov_b32_e32 v87, v168
	v_mov_b32_e32 v89, v172
	v_mov_b32_e32 v95, v122
	v_mov_b32_e32 v97, v128
	v_mov_b32_e32 v99, v130
	v_mov_b32_e32 v103, v170
	v_mov_b32_e32 v105, v174
	v_cvt_pk_bf16_f32 v164, v82, v126
	v_cvt_pk_bf16_f32 v126, v94, v122
	v_cvt_pk_bf16_f32 v127, v96, v128
	v_cvt_pk_bf16_f32 v128, v98, v130
	v_cvt_pk_bf16_f32 v130, v86, v168
	v_cvt_pk_bf16_f32 v131, v88, v172
	v_cvt_pk_bf16_f32 v122, v102, v170
	v_cvt_pk_bf16_f32 v123, v104, v174
	ds_read_b64_tr_b16 v[168:169], v12 offset:26624
	ds_read_b64_tr_b16 v[170:171], v12 offset:27136
	ds_read_b64_tr_b16 v[172:173], v12 offset:30720
	ds_read_b64_tr_b16 v[174:175], v12 offset:31232
	v_cvt_pk_bf16_f32 v163, v80, v124
	v_cvt_pk_bf16_f32 v165, v84, v132
	v_mov_b32_e32 v85, v132
	v_cvt_pk_bf16_f32 v132, v90, v176
	s_waitcnt lgkmcnt(2)
	v_mfma_f32_32x32x16_bf16 v[14:29], v[168:171], v[162:165], v[14:29]
	v_cvt_pk_bf16_f32 v133, v92, v93
	v_cvt_pk_bf16_f32 v129, v100, v150
	v_mov_b32_e32 v81, v124
	v_cvt_pk_bf16_f32 v124, v106, v178
	v_cvt_pk_bf16_f32 v125, v108, v109
	v_mov_b32_e32 v91, v176
	v_mov_b32_e32 v101, v150
	s_waitcnt lgkmcnt(0)
	v_mfma_f32_32x32x16_bf16 v[30:45], v[172:175], v[162:165], v[30:45]
	ds_read_b64_tr_b16 v[162:163], v12 offset:27648
	ds_read_b64_tr_b16 v[164:165], v12 offset:28160
	ds_read_b64_tr_b16 v[168:169], v12 offset:31744
	ds_read_b64_tr_b16 v[170:171], v12 offset:32256
	v_mov_b32_e32 v107, v178
	v_add_f32_e32 v161, v161, v149
	s_waitcnt lgkmcnt(2)
	v_mfma_f32_32x32x16_bf16 v[14:29], v[162:165], v[130:133], v[14:29]
	s_waitcnt lgkmcnt(0)
	v_mfma_f32_32x32x16_bf16 v[30:45], v[168:171], v[130:133], v[30:45]
	ds_read_b64_tr_b16 v[130:131], v12 offset:28672
	ds_read_b64_tr_b16 v[132:133], v12 offset:29184
	ds_read_b64_tr_b16 v[162:163], v12 offset:32768
	ds_read_b64_tr_b16 v[164:165], v12 offset:33280
	s_waitcnt lgkmcnt(2)
	v_mfma_f32_32x32x16_bf16 v[14:29], v[130:133], v[126:129], v[14:29]
	s_waitcnt lgkmcnt(0)
	v_mfma_f32_32x32x16_bf16 v[30:45], v[162:165], v[126:129], v[30:45]
	ds_read_b64_tr_b16 v[126:127], v12 offset:29696
	ds_read_b64_tr_b16 v[128:129], v12 offset:30208
	ds_read_b64_tr_b16 v[130:131], v12 offset:33792
	ds_read_b64_tr_b16 v[132:133], v12 offset:34304
	s_waitcnt lgkmcnt(2)
	v_mfma_f32_32x32x16_bf16 v[14:29], v[126:129], v[122:125], v[14:29]
	s_waitcnt lgkmcnt(0)
	v_mfma_f32_32x32x16_bf16 v[30:45], v[130:133], v[122:125], v[30:45]
	s_cmp_ge_u32 s33, 4
	s_cbranch_scc0 .LBB0_704
	s_andn2_b64 vcc, exec, s[100:101]
	s_cbranch_vccnz .LBB0_704
	s_branch .Lpar_f1_qk

.LBB0_747:
	s_add_i32 s40, s25, 64
	s_cmp_le_i32 s40, s39
	s_cselect_b64 s[4:5], -1, 0
	s_and_b64 s[4:5], s[12:13], s[4:5]
	s_mov_b64 s[98:99], s[4:5]
	s_cmp_ge_u32 s33, 4
	s_cbranch_scc1 .Lpar_m0_c
	s_andn2_b64 vcc, exec, s[4:5]
	s_cbranch_vccnz .LBB0_749
.Lpar_m0_qk:
	ds_read_b128 v[190:193], v162 offset:13312
	ds_read_b128 v[194:197], v162 offset:13344
	ds_read_b128 v[198:201], v162 offset:19968
	ds_read_b128 v[202:205], v162 offset:20000
	ds_read_b128 v[206:209], v162 offset:13376
	ds_read_b128 v[210:213], v162 offset:20032
	ds_read_b128 v[214:217], v162 offset:13408
	ds_read_b128 v[222:225], v162 offset:20064
	ds_read_b128 v[226:229], v162 offset:13440
	ds_read_b128 v[230:233], v162 offset:20096
	ds_read_b128 v[234:237], v162 offset:13472
	ds_read_b128 v[238:241], v162 offset:20128
	s_waitcnt lgkmcnt(11)
	v_mfma_f32_32x32x16_bf16 v[78:93], v[190:193], v[0:3], 0
	s_waitcnt lgkmcnt(10)
	v_mfma_f32_32x32x16_bf16 v[78:93], v[194:197], v[4:7], v[78:93]
	s_waitcnt lgkmcnt(9)
	v_mfma_f32_32x32x16_bf16 v[94:109], v[198:201], v[0:3], 0
	s_waitcnt lgkmcnt(8)
	v_mfma_f32_32x32x16_bf16 v[94:109], v[202:205], v[4:7], v[94:109]
	s_waitcnt lgkmcnt(7)
	v_mfma_f32_32x32x16_bf16 v[78:93], v[206:209], v[8:11], v[78:93]
	s_waitcnt lgkmcnt(6)
	v_mfma_f32_32x32x16_bf16 v[94:109], v[210:213], v[8:11], v[94:109]
	s_waitcnt lgkmcnt(5)
	v_mfma_f32_32x32x16_bf16 v[78:93], v[214:217], v[110:113], v[78:93]
	s_waitcnt lgkmcnt(4)
	v_mfma_f32_32x32x16_bf16 v[94:109], v[222:225], v[110:113], v[94:109]
	s_waitcnt lgkmcnt(3)
	v_mfma_f32_32x32x16_bf16 v[78:93], v[226:229], v[114:117], v[78:93]
	s_waitcnt lgkmcnt(2)
	v_mfma_f32_32x32x16_bf16 v[94:109], v[230:233], v[114:117], v[94:109]
	s_waitcnt lgkmcnt(1)
	v_mfma_f32_32x32x16_bf16 v[78:93], v[234:237], v[118:121], v[78:93]
	s_waitcnt lgkmcnt(0)
	v_mfma_f32_32x32x16_bf16 v[94:109], v[238:241], v[118:121], v[94:109]

.LBB0_752:
	v_sub_f32_e32 v12, v46, v164
	v_exp_f32_e32 v46, v12
	v_sub_f32_e32 v12, v62, v164
	v_exp_f32_e32 v62, v12
	v_sub_f32_e32 v12, v47, v164
	v_sub_f32_e32 v47, v63, v164
	v_exp_f32_e32 v12, v12
	v_exp_f32_e32 v134, v47
	v_add_f32_e32 v135, v62, v46
	v_sub_f32_e32 v47, v48, v164
	v_exp_f32_e32 v48, v47
	v_pk_add_f32 v[136:137], v[134:135], v[12:13]
	v_sub_f32_e32 v47, v64, v164
	v_pk_add_f32 v[136:137], v[136:137], v[136:137] op_sel_hi:[0,1]
	v_exp_f32_e32 v64, v47
	v_sub_f32_e32 v47, v49, v164
	v_exp_f32_e32 v136, v47
	v_sub_f32_e32 v47, v65, v164
	v_exp_f32_e32 v140, v47
	v_add_f32_e32 v141, v64, v48
	v_sub_f32_e32 v47, v50, v164
	v_exp_f32_e32 v50, v47
	v_pk_add_f32 v[138:139], v[140:141], v[136:137]
	v_sub_f32_e32 v47, v66, v164
	v_pk_add_f32 v[138:139], v[138:139], v[138:139] op_sel_hi:[0,1]
	v_exp_f32_e32 v66, v47
	v_sub_f32_e32 v47, v51, v164
	v_exp_f32_e32 v138, v47
	v_sub_f32_e32 v47, v67, v164
	v_exp_f32_e32 v142, v47
	v_add_f32_e32 v143, v66, v50
	v_sub_f32_e32 v47, v52, v164
	v_exp_f32_e32 v52, v47
	v_pk_add_f32 v[144:145], v[142:143], v[138:139]
	v_sub_f32_e32 v47, v68, v164
	v_pk_add_f32 v[144:145], v[144:145], v[144:145] op_sel_hi:[0,1]
	v_exp_f32_e32 v68, v47
	v_sub_f32_e32 v47, v53, v164
	v_exp_f32_e32 v144, v47
	v_sub_f32_e32 v47, v69, v164
	v_exp_f32_e32 v172, v47
	v_add_f32_e32 v173, v68, v52
	v_sub_f32_e32 v47, v54, v164
	v_exp_f32_e32 v54, v47
	v_pk_add_f32 v[168:169], v[172:173], v[144:145]
	v_sub_f32_e32 v47, v70, v164
	v_pk_add_f32 v[174:175], v[168:169], v[168:169] op_sel_hi:[0,1]
	v_exp_f32_e32 v70, v47
	v_sub_f32_e32 v47, v55, v164
	v_exp_f32_e32 v174, v47
	v_sub_f32_e32 v47, v71, v164
	v_exp_f32_e32 v176, v47
	v_add_f32_e32 v177, v70, v54
	v_sub_f32_e32 v47, v56, v164
	v_exp_f32_e32 v56, v47
	v_pk_add_f32 v[168:169], v[176:177], v[174:175]
	v_sub_f32_e32 v47, v72, v164
	v_pk_add_f32 v[178:179], v[168:169], v[168:169] op_sel_hi:[0,1]
	v_exp_f32_e32 v72, v47
	v_sub_f32_e32 v47, v57, v164
	v_exp_f32_e32 v178, v47
	v_sub_f32_e32 v47, v73, v164
	v_exp_f32_e32 v180, v47
	v_add_f32_e32 v181, v72, v56
	v_sub_f32_e32 v47, v58, v164
	v_exp_f32_e32 v58, v47
	v_pk_add_f32 v[168:169], v[180:181], v[178:179]
	v_sub_f32_e32 v47, v74, v164
	v_pk_add_f32 v[182:183], v[168:169], v[168:169] op_sel_hi:[0,1]
	v_exp_f32_e32 v74, v47
	v_sub_f32_e32 v47, v59, v164
	v_exp_f32_e32 v182, v47
	v_sub_f32_e32 v47, v75, v164
	v_exp_f32_e32 v184, v47
	v_sub_f32_e32 v47, v60, v164
	v_exp_f32_e32 v60, v47
	v_sub_f32_e32 v47, v76, v164
	v_exp_f32_e32 v76, v47
	v_sub_f32_e32 v47, v61, v164
	v_sub_f32_e32 v63, v77, v164
	v_exp_f32_e32 v61, v47
	v_exp_f32_e32 v77, v63
	v_add_f32_e32 v185, v74, v58
	v_pk_add_f32 v[168:169], v[184:185], v[182:183]
	v_add_f32_e32 v171, v76, v60
	v_pk_add_f32 v[168:169], v[168:169], v[168:169] op_sel_hi:[0,1]
	v_mov_b32_e32 v170, v77
	v_mov_b32_e32 v168, v61
	v_pk_add_f32 v[168:169], v[170:171], v[168:169]
	v_mov_b32_e32 v47, v12
	v_add_f32_e32 v177, v168, v169
	v_cvt_pk_bf16_f32 v168, v46, v12
	v_add_u32_e32 v12, 0, v161
	v_mov_b32_e32 v55, v174
	v_mov_b32_e32 v57, v178
	v_mov_b32_e32 v65, v140
	v_mov_b32_e32 v67, v142
	v_mov_b32_e32 v69, v172
	v_mov_b32_e32 v73, v180
	v_cvt_pk_bf16_f32 v139, v64, v140
	v_cvt_pk_bf16_f32 v140, v66, v142
	v_cvt_pk_bf16_f32 v141, v68, v172
	v_cvt_pk_bf16_f32 v142, v54, v174
	v_cvt_pk_bf16_f32 v143, v56, v178
	v_cvt_pk_bf16_f32 v135, v72, v180
	ds_read_b64_tr_b16 v[172:173], v12 offset:26624
	ds_read_b64_tr_b16 v[174:175], v12 offset:27136
	ds_read_b64_tr_b16 v[178:179], v12 offset:30720
	ds_read_b64_tr_b16 v[180:181], v12 offset:31232
	v_cvt_pk_bf16_f32 v169, v48, v136
	v_cvt_pk_bf16_f32 v170, v50, v138
	v_cvt_pk_bf16_f32 v171, v52, v144
	v_mov_b32_e32 v53, v144
	v_cvt_pk_bf16_f32 v144, v58, v182
	s_waitcnt lgkmcnt(2)
	v_mfma_f32_32x32x16_bf16 v[14:29], v[172:175], v[168:171], v[14:29]
	v_cvt_pk_bf16_f32 v145, v60, v61
	v_mov_b32_e32 v51, v138
	v_cvt_pk_bf16_f32 v138, v62, v134
	v_mov_b32_e32 v49, v136
	v_mov_b32_e32 v63, v134
	v_cvt_pk_bf16_f32 v134, v70, v176
	v_cvt_pk_bf16_f32 v136, v74, v184
	s_waitcnt lgkmcnt(0)
	v_mfma_f32_32x32x16_bf16 v[30:45], v[178:181], v[168:171], v[30:45]
	ds_read_b64_tr_b16 v[168:169], v12 offset:27648
	ds_read_b64_tr_b16 v[170:171], v12 offset:28160
	ds_read_b64_tr_b16 v[172:173], v12 offset:31744
	ds_read_b64_tr_b16 v[174:175], v12 offset:32256
	v_cvt_pk_bf16_f32 v137, v76, v77
	v_mov_b32_e32 v59, v182
	v_mov_b32_e32 v71, v176
	v_mov_b32_e32 v75, v184
	v_add_f32_e32 v165, v165, v177
	s_waitcnt lgkmcnt(2)
	v_mfma_f32_32x32x16_bf16 v[14:29], v[168:171], v[142:145], v[14:29]
	s_waitcnt lgkmcnt(0)
	v_mfma_f32_32x32x16_bf16 v[30:45], v[172:175], v[142:145], v[30:45]
	ds_read_b64_tr_b16 v[142:143], v12 offset:28672
	ds_read_b64_tr_b16 v[144:145], v12 offset:29184
	ds_read_b64_tr_b16 v[168:169], v12 offset:32768
	ds_read_b64_tr_b16 v[170:171], v12 offset:33280
	s_waitcnt lgkmcnt(2)
	v_mfma_f32_32x32x16_bf16 v[14:29], v[142:145], v[138:141], v[14:29]
	s_waitcnt lgkmcnt(0)
	v_mfma_f32_32x32x16_bf16 v[30:45], v[168:171], v[138:141], v[30:45]
	ds_read_b64_tr_b16 v[138:139], v12 offset:29696
	ds_read_b64_tr_b16 v[140:141], v12 offset:30208
	ds_read_b64_tr_b16 v[142:143], v12 offset:33792
	ds_read_b64_tr_b16 v[144:145], v12 offset:34304
	s_waitcnt lgkmcnt(2)
	v_mfma_f32_32x32x16_bf16 v[14:29], v[138:141], v[134:137], v[14:29]
	s_waitcnt lgkmcnt(0)
	v_mfma_f32_32x32x16_bf16 v[30:45], v[142:145], v[134:137], v[30:45]
	s_cmp_ge_u32 s33, 4
	s_cbranch_scc0 .LBB0_753
	s_andn2_b64 vcc, exec, s[98:99]
	s_cbranch_vccnz .LBB0_753
	s_branch .Lpar_m0_qk

.LBB0_765:
	s_addk_i32 s25, 0x80
	s_cmp_le_i32 s25, s39
	s_cselect_b64 s[14:15], -1, 0
	s_and_b64 s[10:11], s[10:11], s[14:15]
	s_mov_b64 s[100:101], s[10:11]
	s_cmp_ge_u32 s33, 4
	s_cbranch_scc1 .Lpar_m1_c
	s_andn2_b64 vcc, exec, s[10:11]
	s_cbranch_vccnz .LBB0_767
.Lpar_m1_qk:
	ds_read_b128 v[190:193], v162
	ds_read_b128 v[194:197], v162 offset:32
	ds_read_b128 v[198:201], v162 offset:6656
	ds_read_b128 v[202:205], v162 offset:6688
	ds_read_b128 v[206:209], v162 offset:64
	ds_read_b128 v[210:213], v162 offset:6720
	ds_read_b128 v[214:217], v162 offset:96
	ds_read_b128 v[222:225], v162 offset:6752
	ds_read_b128 v[226:229], v162 offset:128
	ds_read_b128 v[230:233], v162 offset:6784
	ds_read_b128 v[234:237], v162 offset:160
	ds_read_b128 v[238:241], v162 offset:6816
	s_waitcnt lgkmcnt(11)
	v_mfma_f32_32x32x16_bf16 v[46:61], v[190:193], v[0:3], 0
	s_waitcnt lgkmcnt(10)
	v_mfma_f32_32x32x16_bf16 v[46:61], v[194:197], v[4:7], v[46:61]
	s_waitcnt lgkmcnt(9)
	v_mfma_f32_32x32x16_bf16 v[62:77], v[198:201], v[0:3], 0
	s_waitcnt lgkmcnt(8)
	v_mfma_f32_32x32x16_bf16 v[62:77], v[202:205], v[4:7], v[62:77]
	s_waitcnt lgkmcnt(7)
	v_mfma_f32_32x32x16_bf16 v[46:61], v[206:209], v[8:11], v[46:61]
	s_waitcnt lgkmcnt(6)
	v_mfma_f32_32x32x16_bf16 v[62:77], v[210:213], v[8:11], v[62:77]
	s_waitcnt lgkmcnt(5)
	v_mfma_f32_32x32x16_bf16 v[46:61], v[214:217], v[110:113], v[46:61]
	s_waitcnt lgkmcnt(4)
	v_mfma_f32_32x32x16_bf16 v[62:77], v[222:225], v[110:113], v[62:77]
	s_waitcnt lgkmcnt(3)
	v_mfma_f32_32x32x16_bf16 v[46:61], v[226:229], v[114:117], v[46:61]
	s_waitcnt lgkmcnt(2)
	v_mfma_f32_32x32x16_bf16 v[62:77], v[230:233], v[114:117], v[62:77]
	s_waitcnt lgkmcnt(1)
	v_mfma_f32_32x32x16_bf16 v[46:61], v[234:237], v[118:121], v[46:61]
	s_waitcnt lgkmcnt(0)
	v_mfma_f32_32x32x16_bf16 v[62:77], v[238:241], v[118:121], v[62:77]

.LBB0_770:
	v_sub_f32_e32 v12, v78, v164
	v_exp_f32_e32 v78, v12
	v_sub_f32_e32 v12, v94, v164
	v_exp_f32_e32 v94, v12
	v_sub_f32_e32 v12, v79, v164
	v_sub_f32_e32 v79, v95, v164
	v_exp_f32_e32 v12, v12
	v_exp_f32_e32 v134, v79
	v_add_f32_e32 v135, v94, v78
	v_sub_f32_e32 v79, v80, v164
	v_exp_f32_e32 v80, v79
	v_pk_add_f32 v[136:137], v[134:135], v[12:13]
	v_sub_f32_e32 v79, v96, v164
	v_pk_add_f32 v[136:137], v[136:137], v[136:137] op_sel_hi:[0,1]
	v_exp_f32_e32 v96, v79
	v_sub_f32_e32 v79, v81, v164
	v_exp_f32_e32 v136, v79
	v_sub_f32_e32 v79, v97, v164
	v_exp_f32_e32 v140, v79
	v_add_f32_e32 v141, v96, v80
	v_sub_f32_e32 v79, v82, v164
	v_exp_f32_e32 v82, v79
	v_pk_add_f32 v[138:139], v[140:141], v[136:137]
	v_sub_f32_e32 v79, v98, v164
	v_pk_add_f32 v[138:139], v[138:139], v[138:139] op_sel_hi:[0,1]
	v_exp_f32_e32 v98, v79
	v_sub_f32_e32 v79, v83, v164
	v_exp_f32_e32 v138, v79
	v_sub_f32_e32 v79, v99, v164
	v_exp_f32_e32 v142, v79
	v_add_f32_e32 v143, v98, v82
	v_sub_f32_e32 v79, v84, v164
	v_exp_f32_e32 v84, v79
	v_pk_add_f32 v[144:145], v[142:143], v[138:139]
	v_sub_f32_e32 v79, v100, v164
	v_pk_add_f32 v[144:145], v[144:145], v[144:145] op_sel_hi:[0,1]
	v_exp_f32_e32 v100, v79
	v_sub_f32_e32 v79, v85, v164
	v_exp_f32_e32 v144, v79
	v_sub_f32_e32 v79, v101, v164
	v_exp_f32_e32 v168, v79
	v_add_f32_e32 v169, v100, v84
	v_sub_f32_e32 v79, v86, v164
	v_exp_f32_e32 v86, v79
	v_pk_add_f32 v[154:155], v[168:169], v[144:145]
	v_sub_f32_e32 v79, v102, v164
	v_pk_add_f32 v[170:171], v[154:155], v[154:155] op_sel_hi:[0,1]
	v_exp_f32_e32 v102, v79
	v_sub_f32_e32 v79, v87, v164
	v_exp_f32_e32 v170, v79
	v_sub_f32_e32 v79, v103, v164
	v_exp_f32_e32 v172, v79
	v_add_f32_e32 v173, v102, v86
	v_sub_f32_e32 v79, v88, v164
	v_exp_f32_e32 v88, v79
	v_pk_add_f32 v[154:155], v[172:173], v[170:171]
	v_sub_f32_e32 v79, v104, v164
	v_pk_add_f32 v[174:175], v[154:155], v[154:155] op_sel_hi:[0,1]
	v_exp_f32_e32 v104, v79
	v_sub_f32_e32 v79, v89, v164
	v_exp_f32_e32 v174, v79
	v_sub_f32_e32 v79, v105, v164
	v_exp_f32_e32 v176, v79
	v_add_f32_e32 v177, v104, v88
	v_sub_f32_e32 v79, v90, v164
	v_exp_f32_e32 v90, v79
	v_pk_add_f32 v[154:155], v[176:177], v[174:175]
	v_sub_f32_e32 v79, v106, v164
	v_pk_add_f32 v[178:179], v[154:155], v[154:155] op_sel_hi:[0,1]
	v_exp_f32_e32 v106, v79
	v_sub_f32_e32 v79, v91, v164
	v_exp_f32_e32 v178, v79
	v_sub_f32_e32 v79, v107, v164
	v_exp_f32_e32 v180, v79
	v_sub_f32_e32 v79, v92, v164
	v_exp_f32_e32 v92, v79
	v_sub_f32_e32 v79, v108, v164
	v_exp_f32_e32 v108, v79
	v_sub_f32_e32 v79, v93, v164
	v_sub_f32_e32 v95, v109, v164
	v_exp_f32_e32 v93, v79
	v_exp_f32_e32 v109, v95
	v_add_f32_e32 v181, v106, v90
	v_pk_add_f32 v[154:155], v[180:181], v[178:179]
	v_add_f32_e32 v157, v108, v92
	v_pk_add_f32 v[154:155], v[154:155], v[154:155] op_sel_hi:[0,1]
	v_mov_b32_e32 v156, v109
	v_mov_b32_e32 v154, v93
	v_pk_add_f32 v[154:155], v[156:157], v[154:155]
	v_mov_b32_e32 v79, v12
	v_add_f32_e32 v177, v154, v155
	v_cvt_pk_bf16_f32 v154, v78, v12
	v_add_u32_e32 v12, 0, v161
	v_mov_b32_e32 v83, v138
	v_mov_b32_e32 v87, v170
	v_mov_b32_e32 v89, v174
	v_mov_b32_e32 v95, v134
	v_mov_b32_e32 v97, v140
	v_mov_b32_e32 v99, v142
	v_mov_b32_e32 v101, v168
	v_mov_b32_e32 v103, v172
	v_cvt_pk_bf16_f32 v156, v82, v138
	v_cvt_pk_bf16_f32 v138, v94, v134
	v_cvt_pk_bf16_f32 v139, v96, v140
	v_cvt_pk_bf16_f32 v140, v98, v142
	v_cvt_pk_bf16_f32 v141, v100, v168
	v_cvt_pk_bf16_f32 v142, v86, v170
	v_cvt_pk_bf16_f32 v143, v88, v174
	v_cvt_pk_bf16_f32 v134, v102, v172
	ds_read_b64_tr_b16 v[168:169], v12 offset:34816
	ds_read_b64_tr_b16 v[170:171], v12 offset:35328
	ds_read_b64_tr_b16 v[172:173], v12 offset:38912
	ds_read_b64_tr_b16 v[174:175], v12 offset:39424
	v_cvt_pk_bf16_f32 v155, v80, v136
	v_cvt_pk_bf16_f32 v157, v84, v144
	v_mov_b32_e32 v85, v144
	v_cvt_pk_bf16_f32 v144, v90, v178
	s_waitcnt lgkmcnt(2)
	v_mfma_f32_32x32x16_bf16 v[14:29], v[168:171], v[154:157], v[14:29]
	v_cvt_pk_bf16_f32 v145, v92, v93
	v_mov_b32_e32 v81, v136
	v_cvt_pk_bf16_f32 v135, v104, v176
	v_cvt_pk_bf16_f32 v136, v106, v180
	v_cvt_pk_bf16_f32 v137, v108, v109
	v_mov_b32_e32 v91, v178
	v_mov_b32_e32 v105, v176
	s_waitcnt lgkmcnt(0)
	v_mfma_f32_32x32x16_bf16 v[30:45], v[172:175], v[154:157], v[30:45]
	ds_read_b64_tr_b16 v[154:155], v12 offset:35840
	ds_read_b64_tr_b16 v[156:157], v12 offset:36352
	ds_read_b64_tr_b16 v[168:169], v12 offset:39936
	ds_read_b64_tr_b16 v[170:171], v12 offset:40448
	v_mov_b32_e32 v107, v180
	v_add_f32_e32 v165, v165, v177
	s_waitcnt lgkmcnt(2)
	v_mfma_f32_32x32x16_bf16 v[14:29], v[154:157], v[142:145], v[14:29]
	s_waitcnt lgkmcnt(0)
	v_mfma_f32_32x32x16_bf16 v[30:45], v[168:171], v[142:145], v[30:45]
	ds_read_b64_tr_b16 v[142:143], v12 offset:36864
	ds_read_b64_tr_b16 v[144:145], v12 offset:37376
	ds_read_b64_tr_b16 v[154:155], v12 offset:40960
	ds_read_b64_tr_b16 v[156:157], v12 offset:41472
	s_waitcnt lgkmcnt(2)
	v_mfma_f32_32x32x16_bf16 v[14:29], v[142:145], v[138:141], v[14:29]
	s_waitcnt lgkmcnt(0)
	v_mfma_f32_32x32x16_bf16 v[30:45], v[154:157], v[138:141], v[30:45]
	ds_read_b64_tr_b16 v[138:139], v12 offset:37888
	ds_read_b64_tr_b16 v[140:141], v12 offset:38400
	ds_read_b64_tr_b16 v[142:143], v12 offset:41984
	ds_read_b64_tr_b16 v[144:145], v12 offset:42496
	s_waitcnt lgkmcnt(2)
	v_mfma_f32_32x32x16_bf16 v[14:29], v[138:141], v[134:137], v[14:29]
	s_waitcnt lgkmcnt(0)
	v_mfma_f32_32x32x16_bf16 v[30:45], v[142:145], v[134:137], v[30:45]
	s_cmp_ge_u32 s33, 4
	s_cbranch_scc0 .LBB0_771
	s_andn2_b64 vcc, exec, s[100:101]
	s_cbranch_vccnz .LBB0_771
	s_branch .Lpar_m1_qk

	.amdhsa_kernel _Z6mk_fwd4Args
		.amdhsa_group_segment_fixed_size 0
		.amdhsa_private_segment_fixed_size 0
		.amdhsa_kernarg_size 384
		.amdhsa_user_sgpr_count 2
		.amdhsa_user_sgpr_dispatch_ptr 0
		.amdhsa_user_sgpr_queue_ptr 0
		.amdhsa_user_sgpr_kernarg_segment_ptr 1
		.amdhsa_user_sgpr_dispatch_id 0
		.amdhsa_user_sgpr_kernarg_preload_length 0
		.amdhsa_user_sgpr_kernarg_preload_offset 0
		.amdhsa_user_sgpr_private_segment_size 0
		.amdhsa_uses_dynamic_stack 0
		.amdhsa_enable_private_segment 0
		.amdhsa_system_sgpr_workgroup_id_x 1
		.amdhsa_system_sgpr_workgroup_id_y 0
		.amdhsa_system_sgpr_workgroup_id_z 0
		.amdhsa_system_sgpr_workgroup_info 0
		.amdhsa_system_vgpr_workitem_id 2
		.amdhsa_next_free_vgpr 256
		.amdhsa_next_free_sgpr 102
		.amdhsa_accum_offset 256
		.amdhsa_reserve_vcc 1
		.amdhsa_float_round_mode_32 0
		.amdhsa_float_round_mode_16_64 0
		.amdhsa_float_denorm_mode_32 3
		.amdhsa_float_denorm_mode_16_64 3
		.amdhsa_dx10_clamp 1
		.amdhsa_ieee_mode 1
		.amdhsa_fp16_overflow 0
		.amdhsa_tg_split 0
		.amdhsa_exception_fp_ieee_invalid_op 0
		.amdhsa_exception_fp_denorm_src 0
		.amdhsa_exception_fp_ieee_div_zero 0
		.amdhsa_exception_fp_ieee_overflow 0
		.amdhsa_exception_fp_ieee_underflow 0
		.amdhsa_exception_fp_ieee_inexact 0
		.amdhsa_exception_int_div_zero 0
	.end_amdhsa_kernel

amdhsa.kernels:
  - .agpr_count:     0
    .args:
      - .offset:         0
        .size:           128
        .value_kind:     by_value
      - .offset:         128
        .size:           4
        .value_kind:     hidden_block_count_x
      - .offset:         132
        .size:           4
        .value_kind:     hidden_block_count_y
      - .offset:         136
        .size:           4
        .value_kind:     hidden_block_count_z
      - .offset:         140
        .size:           2
        .value_kind:     hidden_group_size_x
      - .offset:         142
        .size:           2
        .value_kind:     hidden_group_size_y
      - .offset:         144
        .size:           2
        .value_kind:     hidden_group_size_z
      - .offset:         146
        .size:           2
        .value_kind:     hidden_remainder_x
      - .offset:         148
        .size:           2
        .value_kind:     hidden_remainder_y
      - .offset:         150
        .size:           2
        .value_kind:     hidden_remainder_z
      - .offset:         168
        .size:           8
        .value_kind:     hidden_global_offset_x
      - .offset:         176
        .size:           8
        .value_kind:     hidden_global_offset_y
      - .offset:         184
        .size:           8
        .value_kind:     hidden_global_offset_z
      - .offset:         192
        .size:           2
        .value_kind:     hidden_grid_dims
      - .offset:         216
        .size:           8
        .value_kind:     hidden_multigrid_sync_arg
      - .offset:         248
        .size:           4
        .value_kind:     hidden_dynamic_lds_size
    .group_segment_fixed_size: 0
    .kernarg_segment_align: 8
    .kernarg_segment_size: 384
    .language:       OpenCL C
    .language_version:
      - 2
      - 0
    .max_flat_workgroup_size: 512
    .name:           _Z6mk_fwd4Args
    .private_segment_fixed_size: 0
    .sgpr_count:     108
    .sgpr_spill_count: 138
    .symbol:         _Z6mk_fwd4Args.kd
    .uniform_work_group_size: 1
    .uses_dynamic_stack: false
    .vgpr_count:     256
    .vgpr_spill_count: 0
    .wavefront_size: 64
